# attention main-loop LDS-DMA pieces spread through both iterations (on top of scan o-tile LDS staging + convert_cache spread)
# speedup vs baseline: 1.0168x; 1.0040x over previous
.LBB0_513:
	v_mov_b32_e32 v64, v206
	s_waitcnt vmcnt(0)
	s_barrier
	s_add_i32 s90, s47, s90
	s_add_u32 s100, s10, 0x14000
	s_addc_u32 s101, s11, 0
	s_mov_b32 m0, s90
	v_lshl_add_u64 v[254:255], v[198:199], 0, s[100:101]
	global_load_lds_dwordx4 v[254:255], off
.LBB0_515:
	v_ashrrev_i32_e32 v65, 5, v64
	v_lshlrev_b32_e32 v66, 8, v64
	v_add_u32_e32 v67, s49, v65
	v_bfe_u32 v172, v64, 2, 2
	v_and_b32_e32 v66, 0x1f00, v66
	v_bitop3_b32 v67, v67, v64, 15 bitop3:0x78
	v_lshlrev_b32_e32 v68, 4, v67
	v_lshlrev_b32_e32 v193, 10, v65
	v_lshlrev_b32_e32 v195, 8, v172
	v_lshrrev_b32_e32 v65, 3, v64
	v_bfe_u32 v67, v64, 1, 1
	s_xor_b32 s58, s75, 0x10000
	v_and_or_b32 v65, v65, 2, v67
	v_lshlrev_b32_e32 v64, 3, v64
	s_add_i32 s58, s58, 0
	v_lshlrev_b32_e32 v239, 4, v65
	v_and_b32_e32 v240, 8, v64
	v_add_u32_e32 v69, s58, v66
	v_add_u32_e32 v70, v69, v68
	ds_read_b128 v[64:67], v70
	ds_read_b128 v[160:163], v70 offset:8192
	v_xad_u32 v70, v68, 32, v69
	ds_read_b128 v[144:147], v70
	ds_read_b128 v[164:167], v70 offset:8192
	v_xad_u32 v70, v68, 64, v69
	v_xad_u32 v68, v68, s4, v69
	ds_read_b128 v[148:151], v70
	ds_read_b128 v[168:171], v70 offset:8192
	ds_read_b128 v[152:155], v68
	ds_read_b128 v[156:159], v68 offset:8192
	s_waitcnt lgkmcnt(7)
	v_mfma_f32_32x32x16_bf16 v[64:79], v[64:67], v[112:115], 0
	v_lshlrev_b32_e32 v172, 6, v172
	s_waitcnt lgkmcnt(5)
	v_mfma_f32_32x32x16_bf16 v[64:79], v[144:147], v[136:139], v[64:79]
	v_add3_u32 v144, s74, v193, v195
	v_add3_u32 v193, v144, v239, v240
	v_add_u32_e32 v195, v193, v172
	ds_read_b64_tr_b16 v[144:145], v195 offset:16384
	ds_read_b64_tr_b16 v[146:147], v195 offset:18432
	ds_read_b64_tr_b16 v[240:241], v195 offset:28672
	ds_read_b64_tr_b16 v[242:243], v195 offset:30720
	s_waitcnt lgkmcnt(7)
	v_mfma_f32_32x32x16_bf16 v[64:79], v[148:151], v[132:135], v[64:79]
	ds_read_b64_tr_b16 v[148:149], v195 offset:20480
	ds_read_b64_tr_b16 v[150:151], v195 offset:22528
	s_waitcnt lgkmcnt(7)
	v_mfma_f32_32x32x16_bf16 v[64:79], v[152:155], v[128:131], v[64:79]
	ds_read_b64_tr_b16 v[152:153], v195 offset:24576
	ds_read_b64_tr_b16 v[154:155], v195 offset:26624
	v_xad_u32 v195, v172, 64, v193
	s_waitcnt lgkmcnt(6)
	v_mfma_f32_32x32x16_bf16 v[48:63], v[144:147], v[116:119], v[48:63]
	ds_read_b64_tr_b16 v[144:145], v195 offset:16384
	ds_read_b64_tr_b16 v[146:147], v195 offset:18432
	s_waitcnt lgkmcnt(4)
	v_mfma_f32_32x32x16_bf16 v[48:63], v[148:151], v[120:123], v[48:63]
	v_lshl_add_u64 v[254:255], v[200:201], 0, s[100:101]
	global_load_lds_dwordx4 v[254:255], off offset:1024
	ds_read_b64_tr_b16 v[148:149], v195 offset:20480
	ds_read_b64_tr_b16 v[150:151], v195 offset:22528
	s_waitcnt lgkmcnt(4)
	v_mfma_f32_32x32x16_bf16 v[48:63], v[152:155], v[124:127], v[48:63]
	ds_read_b64_tr_b16 v[152:153], v195 offset:24576
	ds_read_b64_tr_b16 v[154:155], v195 offset:26624
	v_mfma_f32_32x32x16_bf16 v[48:63], v[240:243], v[140:143], v[48:63]
	ds_read_b64_tr_b16 v[240:241], v195 offset:28672
	ds_read_b64_tr_b16 v[242:243], v195 offset:30720
	v_xad_u32 v195, v172, s5, v193
	v_xad_u32 v172, v172, s33, v193
	s_waitcnt lgkmcnt(6)
	v_mfma_f32_32x32x16_bf16 v[32:47], v[144:147], v[116:119], v[32:47]
	ds_read_b64_tr_b16 v[144:145], v195 offset:16384
	ds_read_b64_tr_b16 v[146:147], v195 offset:18432
	s_waitcnt lgkmcnt(6)
	v_mfma_f32_32x32x16_bf16 v[32:47], v[148:151], v[120:123], v[32:47]
	ds_read_b64_tr_b16 v[148:149], v195 offset:20480
	ds_read_b64_tr_b16 v[150:151], v195 offset:22528
	s_waitcnt lgkmcnt(6)
	v_mfma_f32_32x32x16_bf16 v[32:47], v[152:155], v[124:127], v[32:47]
	ds_read_b64_tr_b16 v[152:153], v195 offset:24576
	ds_read_b64_tr_b16 v[154:155], v195 offset:26624
	s_waitcnt lgkmcnt(6)
	v_mfma_f32_32x32x16_bf16 v[32:47], v[240:243], v[140:143], v[32:47]
	v_lshl_add_u64 v[254:255], v[202:203], 0, s[100:101]
	global_load_lds_dwordx4 v[254:255], off offset:2048
	ds_read_b64_tr_b16 v[240:241], v195 offset:28672
	ds_read_b64_tr_b16 v[242:243], v195 offset:30720
	s_waitcnt lgkmcnt(6)
	v_mfma_f32_32x32x16_bf16 v[16:31], v[144:147], v[116:119], v[16:31]
	ds_read_b64_tr_b16 v[144:145], v172 offset:16384
	ds_read_b64_tr_b16 v[146:147], v172 offset:18432
	s_waitcnt lgkmcnt(6)
	v_mfma_f32_32x32x16_bf16 v[16:31], v[148:151], v[120:123], v[16:31]
	ds_read_b64_tr_b16 v[148:149], v172 offset:20480
	ds_read_b64_tr_b16 v[150:151], v172 offset:22528
	s_waitcnt lgkmcnt(6)
	v_mfma_f32_32x32x16_bf16 v[16:31], v[152:155], v[124:127], v[16:31]
	ds_read_b64_tr_b16 v[152:153], v172 offset:24576
	ds_read_b64_tr_b16 v[154:155], v172 offset:26624
	s_waitcnt lgkmcnt(6)
	v_mfma_f32_32x32x16_bf16 v[16:31], v[240:243], v[140:143], v[16:31]
	ds_read_b64_tr_b16 v[240:241], v172 offset:28672
	ds_read_b64_tr_b16 v[242:243], v172 offset:30720
	s_waitcnt lgkmcnt(6)
	v_mfma_f32_32x32x16_bf16 v[0:15], v[144:147], v[116:119], v[0:15]
	v_max_f32_e32 v116, v97, v97
	v_max_f32_e32 v117, v96, v96
	v_max_f32_e32 v116, v117, v116
	v_max3_f32 v116, v116, v98, v99
	v_max3_f32 v116, v116, v100, v101
	v_max3_f32 v116, v116, v102, v103
	v_max3_f32 v116, v116, v104, v105
	v_max3_f32 v116, v116, v106, v107
	v_max3_f32 v116, v116, v108, v109
	v_max3_f32 v116, v116, v110, v111
	v_max3_f32 v116, v116, v80, v81
	v_max3_f32 v116, v116, v82, v83
	v_max3_f32 v116, v116, v84, v85
	v_max3_f32 v116, v116, v86, v87
	v_max3_f32 v116, v116, v88, v89
	v_max3_f32 v116, v116, v90, v91
	v_max3_f32 v116, v116, v92, v93
	v_max3_f32 v116, v116, v94, v95
	ds_bpermute_b32 v117, v191, v116
	s_waitcnt lgkmcnt(0)
	v_max3_f32 v193, v197, v116, v117
	v_sub_f32_e32 v80, v80, v193
	v_mfma_f32_32x32x16_bf16 v[0:15], v[148:151], v[120:123], v[0:15]
	v_lshl_add_u64 v[254:255], v[204:205], 0, s[100:101]
	global_load_lds_dwordx4 v[254:255], off offset:3072
	v_exp_f32_e32 v121, v80
	v_sub_f32_e32 v80, v97, v193
	v_exp_f32_e32 v116, v80
	v_sub_f32_e32 v80, v81, v193
	v_sub_f32_e32 v96, v96, v193
	v_exp_f32_e32 v120, v96
	v_exp_f32_e32 v172, v80
	v_add_f32_e32 v117, v120, v121
	v_pk_add_f32 v[80:81], v[116:117], v[172:173]
	s_nop 0
	v_pk_add_f32 v[80:81], v[80:81], v[80:81] op_sel_hi:[0,1]
	v_sub_f32_e32 v80, v98, v193
	v_exp_f32_e32 v97, v80
	v_sub_f32_e32 v80, v82, v193
	v_exp_f32_e32 v117, v80
	v_sub_f32_e32 v80, v99, v193
	v_exp_f32_e32 v118, v80
	v_sub_f32_e32 v80, v83, v193
	v_exp_f32_e32 v80, v80
	v_add_f32_e32 v119, v97, v117
	v_pk_add_f32 v[82:83], v[118:119], v[80:81]
	s_nop 0
	v_pk_add_f32 v[82:83], v[82:83], v[82:83] op_sel_hi:[0,1]
	v_sub_f32_e32 v82, v84, v193
	v_exp_f32_e32 v119, v82
	v_sub_f32_e32 v82, v101, v193
	v_exp_f32_e32 v98, v82
	v_sub_f32_e32 v82, v85, v193
	v_sub_f32_e32 v81, v100, v193
	v_exp_f32_e32 v81, v81
	v_exp_f32_e32 v82, v82
	v_add_f32_e32 v99, v81, v119
	v_pk_add_f32 v[84:85], v[98:99], v[82:83]
	v_sub_f32_e32 v83, v102, v193
	v_pk_add_f32 v[84:85], v[84:85], v[84:85] op_sel_hi:[0,1]
	v_sub_f32_e32 v84, v86, v193
	v_exp_f32_e32 v99, v84
	v_sub_f32_e32 v84, v103, v193
	v_exp_f32_e32 v83, v83
	v_exp_f32_e32 v100, v84
	v_sub_f32_e32 v84, v87, v193
	v_exp_f32_e32 v84, v84
	v_add_f32_e32 v101, v83, v99
	v_pk_add_f32 v[86:87], v[100:101], v[84:85]
	s_nop 0
	v_pk_add_f32 v[86:87], v[86:87], v[86:87] op_sel_hi:[0,1]
	v_sub_f32_e32 v86, v88, v193
	v_exp_f32_e32 v101, v86
	v_sub_f32_e32 v86, v105, v193
	v_exp_f32_e32 v102, v86
	v_sub_f32_e32 v86, v89, v193
	v_exp_f32_e32 v86, v86
	v_mfma_f32_32x32x16_bf16 v[0:15], v[152:155], v[124:127], v[0:15]
	v_cvt_pk_bf16_f32 v152, v101, v86
	v_sub_f32_e32 v85, v104, v193
	v_exp_f32_e32 v85, v85
	s_nop 0
	v_add_f32_e32 v103, v85, v101
	v_pk_add_f32 v[88:89], v[102:103], v[86:87]
	s_nop 0
	v_pk_add_f32 v[88:89], v[88:89], v[88:89] op_sel_hi:[0,1]
	v_sub_f32_e32 v88, v90, v193
	v_exp_f32_e32 v103, v88
	v_sub_f32_e32 v88, v107, v193
	v_exp_f32_e32 v104, v88
	v_sub_f32_e32 v88, v91, v193
	v_exp_f32_e32 v88, v88
	s_nop 0
	v_cvt_pk_bf16_f32 v153, v103, v88
	v_sub_f32_e32 v87, v106, v193
	v_exp_f32_e32 v87, v87
	s_nop 0
	v_add_f32_e32 v105, v87, v103
	v_pk_add_f32 v[90:91], v[104:105], v[88:89]
	s_nop 0
	v_pk_add_f32 v[90:91], v[90:91], v[90:91] op_sel_hi:[0,1]
	v_sub_f32_e32 v90, v92, v193
	v_exp_f32_e32 v105, v90
	v_sub_f32_e32 v90, v109, v193
	v_exp_f32_e32 v106, v90
	v_sub_f32_e32 v90, v93, v193
	v_exp_f32_e32 v90, v90
	s_nop 0
	v_cvt_pk_bf16_f32 v154, v105, v90
	v_sub_f32_e32 v89, v108, v193
	v_exp_f32_e32 v89, v89
	s_nop 0
	v_add_f32_e32 v107, v89, v105
	v_pk_add_f32 v[92:93], v[106:107], v[90:91]
	s_nop 0
	v_pk_add_f32 v[92:93], v[92:93], v[92:93] op_sel_hi:[0,1]
	v_sub_f32_e32 v92, v94, v193
	v_exp_f32_e32 v107, v92
	v_sub_f32_e32 v92, v111, v193
	v_exp_f32_e32 v108, v92
	v_sub_f32_e32 v92, v95, v193
	v_exp_f32_e32 v92, v92
	s_nop 0
	v_cvt_pk_bf16_f32 v155, v107, v92
	v_cvt_pk_bf16_f32 v146, v119, v82
	v_cvt_pk_bf16_f32 v147, v99, v84
	v_cvt_pk_bf16_f32 v149, v87, v104
	v_cvt_pk_bf16_f32 v150, v89, v106
	v_cvt_pk_bf16_f32 v144, v121, v172
	v_cvt_pk_bf16_f32 v145, v117, v80
	v_sub_f32_e32 v91, v110, v193
	v_exp_f32_e32 v91, v91
	s_nop 0
	v_cvt_pk_bf16_f32 v151, v91, v108
	v_cvt_pk_bf16_f32 v148, v85, v102
	v_mfma_f32_32x32x16_bf16 v[0:15], v[240:243], v[140:143], v[0:15]
	v_cvt_pk_bf16_f32 v141, v97, v118
	v_cvt_pk_bf16_f32 v142, v81, v98
	v_cvt_pk_bf16_f32 v143, v83, v100
	v_cvt_pk_bf16_f32 v140, v120, v116
	v_add_f32_e32 v109, v91, v107
	v_pk_add_f32 v[94:95], v[108:109], v[92:93]
	v_sub_f32_e32 v93, v197, v193
	v_add_f32_e32 v195, v94, v95
	v_exp_f32_e32 v96, v93
	v_mfma_f32_32x32x16_bf16 v[80:95], v[160:163], v[112:115], 0
	v_fmac_f32_e32 v195, v238, v96
	v_cmp_neq_f32_e32 vcc, 1.0, v96
	v_mfma_f32_32x32x16_bf16 v[80:95], v[164:167], v[136:139], v[80:95]
	v_mfma_f32_32x32x16_bf16 v[80:95], v[168:171], v[132:135], v[80:95]
	v_mfma_f32_32x32x16_bf16 v[80:95], v[156:159], v[128:131], v[80:95]
	s_cbranch_vccz .LBB0_508
	v_pk_mul_f32 v[62:63], v[62:63], v[96:97] op_sel_hi:[1,0]
	v_pk_mul_f32 v[60:61], v[60:61], v[96:97] op_sel_hi:[1,0]
	v_pk_mul_f32 v[58:59], v[58:59], v[96:97] op_sel_hi:[1,0]
	v_pk_mul_f32 v[56:57], v[56:57], v[96:97] op_sel_hi:[1,0]
	v_pk_mul_f32 v[54:55], v[54:55], v[96:97] op_sel_hi:[1,0]
	v_pk_mul_f32 v[52:53], v[52:53], v[96:97] op_sel_hi:[1,0]
	v_pk_mul_f32 v[50:51], v[50:51], v[96:97] op_sel_hi:[1,0]
	v_pk_mul_f32 v[48:49], v[48:49], v[96:97] op_sel_hi:[1,0]
	v_pk_mul_f32 v[46:47], v[46:47], v[96:97] op_sel_hi:[1,0]
	v_pk_mul_f32 v[44:45], v[44:45], v[96:97] op_sel_hi:[1,0]
	v_pk_mul_f32 v[42:43], v[42:43], v[96:97] op_sel_hi:[1,0]
	v_pk_mul_f32 v[40:41], v[40:41], v[96:97] op_sel_hi:[1,0]
	v_pk_mul_f32 v[38:39], v[38:39], v[96:97] op_sel_hi:[1,0]
	v_pk_mul_f32 v[36:37], v[36:37], v[96:97] op_sel_hi:[1,0]
	v_pk_mul_f32 v[34:35], v[34:35], v[96:97] op_sel_hi:[1,0]
	v_pk_mul_f32 v[32:33], v[32:33], v[96:97] op_sel_hi:[1,0]
	v_pk_mul_f32 v[30:31], v[30:31], v[96:97] op_sel_hi:[1,0]
	v_pk_mul_f32 v[28:29], v[28:29], v[96:97] op_sel_hi:[1,0]
	v_pk_mul_f32 v[26:27], v[26:27], v[96:97] op_sel_hi:[1,0]
	v_pk_mul_f32 v[24:25], v[24:25], v[96:97] op_sel_hi:[1,0]
	v_pk_mul_f32 v[22:23], v[22:23], v[96:97] op_sel_hi:[1,0]
	v_pk_mul_f32 v[20:21], v[20:21], v[96:97] op_sel_hi:[1,0]
	v_pk_mul_f32 v[18:19], v[18:19], v[96:97] op_sel_hi:[1,0]
	v_pk_mul_f32 v[16:17], v[16:17], v[96:97] op_sel_hi:[1,0]
	v_pk_mul_f32 v[14:15], v[14:15], v[96:97] op_sel_hi:[1,0]
	v_pk_mul_f32 v[12:13], v[12:13], v[96:97] op_sel_hi:[1,0]
	v_pk_mul_f32 v[10:11], v[10:11], v[96:97] op_sel_hi:[1,0]
	v_pk_mul_f32 v[8:9], v[8:9], v[96:97] op_sel_hi:[1,0]
	v_pk_mul_f32 v[6:7], v[6:7], v[96:97] op_sel_hi:[1,0]
	v_pk_mul_f32 v[4:5], v[4:5], v[96:97] op_sel_hi:[1,0]
	v_pk_mul_f32 v[2:3], v[2:3], v[96:97] op_sel_hi:[1,0]
	v_pk_mul_f32 v[0:1], v[0:1], v[96:97] op_sel_hi:[1,0]
	s_branch .LBB0_508
